# attention phases: one static s_setprio 1 for waves 4-7 (younger half), reset at phase end
# baseline (speedup 1.0000x reference)
; __global__ void __launch_bounds__(NWAVES * 64, 2) mk_fwd(Args args) {
;     ...
;     if (IN(2)) { constexpr int l = 0; const unsigned char* wl = ws + WS_W + l * W_LAYER; (void)wl;
;                 float lam, oml;
;                 { const float a = args.in[7][64 * l + lane] * args.in[8][64 * l + lane], b = args.in[9][64 * l + lane] * args.in[10][64 * l + lane];
;                   const float sa = wave_sum(a), sb = wave_sum(b); const float li = (l == 0) ? 0.2f : 0.35550906759096934f;
;                   lam = __builtin_amdgcn_exp2f(sa * 1.4426950408889634f) - __builtin_amdgcn_exp2f(sb * 1.4426950408889634f) + li; oml = 1.0f - li; }
;                 float mfix;
;                 { float a = __builtin_fabsf(args.in[5][64 * l + lane]), b = __builtin_fabsf(args.in[6][64 * l + lane]);
; #pragma unroll
;                   for (int o = 1; o < 64; o <<= 1) { a = __builtin_fmaxf(a, __shfl_xor(a, o)); b = __builtin_fmaxf(b, __shfl_xor(b, o)); }
;                   mfix = 0.125f * 1.4426950408889634f * 64.0f * 1.01f * a * b; }
;                 bf16* scrg = (bf16*)(ws + WS_SCR) + (size_t)bx * (256 * 256);
;                 const float* gsub = args.in[11] + 128 * l;
;                 for (int i = 0;; ++i) {
;                     const int u = i * G + vcu; if (u >= 3840) break;
;                     int b, h, qb, rowbase, NT; bool diff;
;                     if (u < 256) { b = u >> 6; h = (u >> 4) & 3; qb = u & 15; rowbase = TP + b * 4096; NT = 64; diff = true; }
;                     else if (u < 1280) { const int v = u - 256; b = v >> 5; h = (v >> 3) & 3; qb = v & 7; rowbase = b * 2048; NT = 32; diff = true; }
;                     else if (u < 1792) { const int v = u - 1280; b = v >> 7; h = (v >> 4) & 7; qb = v & 15; rowbase = TP + b * 4096; NT = 64; diff = false; }
;                     else { const int v = u - 1792; b = v >> 6; h = (v >> 3) & 7; qb = v & 7; rowbase = b * 2048; NT = 32; diff = false; }
;                     const int q0 = qb * 256;
;                     const size_t rq = (size_t)(rowbase + q0) * 64, rk = (size_t)rowbase * 64; constexpr size_t SL = (size_t)T * 64;
;                     if (!diff) {
;                         attn_body::attn_unit<8>((const attn_body::bf16*)(PROJ + h * SL + rq), (const attn_body::bf16*)(PROJ + (8 + (h >> 2)) * SL + rk), (const attn_body::bf16*)(PROJ + (10 + (h >> 2)) * SL + rk),
.LBB0_267:
	s_cmp_lt_i32 s58, 3
	s_cselect_b64 s[0:1], -1, 0
	s_add_u32 s36, s54, 0x25c00000
	s_addc_u32 s37, s55, 0
	s_and_b64 s[0:1], s[0:1], s[4:5]
	s_andn2_b64 vcc, exec, s[0:1]
	v_lshlrev_b32_e32 v238, 2, v214
	v_lshrrev_b32_e32 v239, 1, v214
	s_cbranch_vccnz .LBB0_367
	v_readlane_b32 s8, v255, 22
	s_nop 1
	s_cmp_lt_u32 s8, 4
	s_cbranch_scc1 .Lprio_skip0
	s_setprio 1
.Lprio_skip0:
	v_readlane_b32 s8, v255, 6
	global_load_dword v3, v238, s[50:51]
	v_readlane_b32 s9, v255, 7
	v_readlane_b32 s10, v255, 8
	v_readlane_b32 s11, v255, 9
	v_readlane_b32 s12, v255, 10
	v_readlane_b32 s13, v255, 11
	s_nop 0
	global_load_dword v6, v238, s[8:9]
	s_nop 0
	global_load_dword v7, v238, s[10:11]
	s_nop 0
	global_load_dword v8, v238, s[12:13]
	global_load_dword v9, v238, s[46:47]
	global_load_dword v10, v238, s[48:49]
	v_mbcnt_lo_u32_b32 v0, -1, 0
	v_mbcnt_hi_u32_b32 v4, -1, v0
	v_and_b32_e32 v5, 64, v4
	v_xor_b32_e32 v11, 1, v4
	v_add_u32_e32 v5, 64, v5
	v_xor_b32_e32 v12, 2, v4
	v_cmp_lt_i32_e32 vcc, v11, v5
	s_ashr_i32 s3, s2, 31
	v_readlane_b32 s4, v255, 22
	v_xor_b32_e32 v13, 4, v4
	v_cndmask_b32_e32 v11, v4, v11, vcc
	v_cmp_lt_i32_e32 vcc, v12, v5
	v_lshl_or_b32 v239, s4, 5, v239
	s_lshl_b64 s[4:5], s[2:3], 17
	v_xor_b32_e32 v14, 8, v4
	v_cndmask_b32_e32 v12, v4, v12, vcc
	v_cmp_lt_i32_e32 vcc, v13, v5
	v_xor_b32_e32 v15, 16, v4
	s_add_u32 s3, s54, s4
	v_cndmask_b32_e32 v13, v4, v13, vcc
	v_cmp_lt_i32_e32 vcc, v14, v5
	v_xor_b32_e32 v16, 32, v4
	s_addc_u32 s4, s55, s5
	v_cndmask_b32_e32 v14, v4, v14, vcc
	v_cmp_lt_i32_e32 vcc, v15, v5
	s_waitcnt lgkmcnt(0)
	v_lshlrev_b32_e32 v1, 6, v215
	s_add_u32 s10, s3, 0x3400000
	v_cndmask_b32_e32 v15, v4, v15, vcc
	v_cmp_lt_i32_e32 vcc, v16, v5
	v_and_b32_e32 v2, 64, v1
	v_mov_b32_e32 v1, 0
	v_lshlrev_b32_e32 v0, 9, v239
	v_cndmask_b32_e32 v4, v4, v16, vcc
	s_addc_u32 s11, s4, 0
	v_lshlrev_b32_e32 v240, 2, v11
	v_lshlrev_b32_e32 v11, 2, v12
	v_lshlrev_b32_e32 v12, 2, v13
	v_lshlrev_b32_e32 v13, 2, v14
	v_lshlrev_b32_e32 v14, 2, v15
	v_lshlrev_b32_e32 v15, 2, v4
	v_lshl_add_u64 v[4:5], s[10:11], 0, v[0:1]
	v_lshlrev_b32_e32 v0, 1, v2
	v_lshl_add_u64 v[216:217], v[4:5], 0, v[0:1]
	v_readlane_b32 s14, v255, 12
	v_readlane_b32 s15, v255, 13
	s_add_u32 s3, s54, 0x80000
	s_movk_i32 s12, 0xe000
	s_mov_b32 s9, 0
	s_addc_u32 s35, s55, 0
	s_mov_b32 s13, -1
	s_mov_b64 s[38:39], 0x4000
	s_mov_b64 s[40:41], 0x2000
	s_mov_b32 s84, 0xffff0000
	s_mov_b64 s[42:43], 0x6000
	s_mov_b64 s[44:45], 0x8000
	s_mov_b64 s[64:65], 0xa000
	v_mov_b32_e32 v242, 0x3727c5ac
	v_lshlrev_b32_e32 v222, 1, v2
	s_movk_i32 s85, 0x7fff
	s_mov_b32 s86, 0
	v_readlane_b32 s16, v255, 14
	v_readlane_b32 s17, v255, 15
	v_readlane_b32 s18, v255, 16
	v_readlane_b32 s19, v255, 17
	v_readlane_b32 s20, v255, 18
	v_readlane_b32 s21, v255, 19
	v_readlane_b32 s22, v255, 20
	v_readlane_b32 s23, v255, 21
	s_waitcnt vmcnt(4)
	v_mul_f32_e32 v0, v3, v6
	ds_bpermute_b32 v0, v240, v0
	s_waitcnt vmcnt(2)
	v_mul_f32_e32 v4, v7, v8
	s_waitcnt vmcnt(1)
	v_and_b32_e32 v5, 0x7fffffff, v9
	s_waitcnt vmcnt(0)
	v_and_b32_e32 v16, 0x7fffffff, v10
	ds_bpermute_b32 v4, v240, v4
	ds_bpermute_b32 v5, v240, v5
	ds_bpermute_b32 v16, v240, v16
	v_max_f32_e64 v9, |v9|, |v9|
	s_waitcnt lgkmcnt(3)
	v_fmac_f32_e32 v0, v3, v6
	s_waitcnt lgkmcnt(2)
	v_fmac_f32_e32 v4, v7, v8
	s_waitcnt lgkmcnt(1)
	v_max_f32_e32 v3, v5, v5
	v_max_f32_e64 v10, |v10|, |v10|
	s_waitcnt lgkmcnt(0)
	v_max_f32_e32 v5, v16, v16
	ds_bpermute_b32 v6, v11, v0
	ds_bpermute_b32 v7, v11, v4
	v_max_f32_e32 v3, v9, v3
	v_max_f32_e32 v5, v10, v5
	ds_bpermute_b32 v8, v11, v3
	ds_bpermute_b32 v9, v11, v5
	s_waitcnt lgkmcnt(3)
	v_add_f32_e32 v0, v0, v6
	s_waitcnt lgkmcnt(2)
	v_add_f32_e32 v4, v4, v7
	ds_bpermute_b32 v6, v12, v0
	ds_bpermute_b32 v7, v12, v4
	s_waitcnt lgkmcnt(3)
	v_max_f32_e32 v8, v8, v8
	s_waitcnt lgkmcnt(2)
	v_max_f32_e32 v9, v9, v9
	v_max_f32_e32 v3, v3, v8
	v_max_f32_e32 v5, v5, v9
	ds_bpermute_b32 v8, v12, v3
	ds_bpermute_b32 v9, v12, v5
	s_waitcnt lgkmcnt(3)
	v_add_f32_e32 v0, v0, v6
	s_waitcnt lgkmcnt(2)
	v_add_f32_e32 v4, v4, v7
	ds_bpermute_b32 v6, v13, v0
	ds_bpermute_b32 v7, v13, v4
	s_waitcnt lgkmcnt(3)
	v_max_f32_e32 v8, v8, v8
	s_waitcnt lgkmcnt(2)
	v_max_f32_e32 v9, v9, v9
	v_max_f32_e32 v3, v3, v8
	v_max_f32_e32 v5, v5, v9
	ds_bpermute_b32 v8, v13, v3
	ds_bpermute_b32 v9, v13, v5
	s_waitcnt lgkmcnt(3)
	v_add_f32_e32 v0, v0, v6
	s_waitcnt lgkmcnt(2)
	v_add_f32_e32 v4, v4, v7
	ds_bpermute_b32 v6, v14, v0
	ds_bpermute_b32 v7, v14, v4
	s_waitcnt lgkmcnt(3)
	v_max_f32_e32 v8, v8, v8
	s_waitcnt lgkmcnt(2)
	v_max_f32_e32 v9, v9, v9
	v_max_f32_e32 v3, v3, v8
	v_max_f32_e32 v5, v5, v9
	ds_bpermute_b32 v8, v14, v3
	ds_bpermute_b32 v9, v14, v5
	s_waitcnt lgkmcnt(3)
	v_add_f32_e32 v0, v0, v6
	s_waitcnt lgkmcnt(2)
	v_add_f32_e32 v4, v4, v7
	ds_bpermute_b32 v6, v15, v0
	ds_bpermute_b32 v7, v15, v4
	s_waitcnt lgkmcnt(3)
	v_max_f32_e32 v8, v8, v8
	s_waitcnt lgkmcnt(2)
	v_max_f32_e32 v9, v9, v9
	v_max_f32_e32 v3, v3, v8
	v_max_f32_e32 v5, v5, v9
	s_waitcnt lgkmcnt(1)
	v_add_f32_e32 v0, v0, v6
	s_waitcnt lgkmcnt(0)
	v_add_f32_e32 v4, v4, v7
	ds_bpermute_b32 v6, v15, v3
	ds_bpermute_b32 v7, v15, v5
	v_mul_f32_e32 v0, 0x3fb8aa3b, v0
	v_mul_f32_e32 v4, 0x3fb8aa3b, v4
	v_exp_f32_e32 v8, v0
	v_exp_f32_e32 v4, v4
	s_waitcnt lgkmcnt(1)
	v_max_f32_e32 v6, v6, v6
	s_waitcnt lgkmcnt(0)
	v_max_f32_e32 v7, v7, v7
	v_max_f32_e32 v3, v3, v6
	v_sub_f32_e32 v4, v8, v4
	v_lshlrev_b32_e32 v0, 2, v2
	v_max_f32_e32 v5, v5, v7
	v_add_f32_e32 v218, 0x3e4ccccd, v4
	v_mul_f32_e32 v3, 0x413a82f9, v3
	v_mul_f32_e32 v241, v5, v3
	v_lshl_add_u64 v[220:221], s[14:15], 0, v[0:1]
	v_mov_b32_e32 v219, v218
	s_branch .LBB0_270

; __global__ void __launch_bounds__(NWAVES * 64, 2) mk_fwd(Args args) {
;     ...
;                 }
;     }
.LBB0_366:
	s_setprio 0
	v_lshrrev_b32_e32 v239, 1, v214

; __global__ void __launch_bounds__(NWAVES * 64, 2) mk_fwd(Args args) {
;     ...
;     if (IN(7)) { constexpr int l = 1; const unsigned char* wl = ws + WS_W + l * W_LAYER; (void)wl;
;                 float lam, oml;
;                 { const float a = args.in[7][64 * l + lane] * args.in[8][64 * l + lane], b = args.in[9][64 * l + lane] * args.in[10][64 * l + lane];
;                   const float sa = wave_sum(a), sb = wave_sum(b); const float li = (l == 0) ? 0.2f : 0.35550906759096934f;
;                   lam = __builtin_amdgcn_exp2f(sa * 1.4426950408889634f) - __builtin_amdgcn_exp2f(sb * 1.4426950408889634f) + li; oml = 1.0f - li; }
;                 float mfix;
;                 { float a = __builtin_fabsf(args.in[5][64 * l + lane]), b = __builtin_fabsf(args.in[6][64 * l + lane]);
; #pragma unroll
;                   for (int o = 1; o < 64; o <<= 1) { a = __builtin_fmaxf(a, __shfl_xor(a, o)); b = __builtin_fmaxf(b, __shfl_xor(b, o)); }
;                   mfix = 0.125f * 1.4426950408889634f * 64.0f * 1.01f * a * b; }
;                 bf16* scrg = (bf16*)(ws + WS_SCR) + (size_t)bx * (256 * 256);
;                 const float* gsub = args.in[11] + 128 * l;
;                 for (int i = 0;; ++i) {
;                     const int u = i * G + vcu; if (u >= 3840) break;
;                     int b, h, qb, rowbase, NT; bool diff;
;                     if (u < 256) { b = u >> 6; h = (u >> 4) & 3; qb = u & 15; rowbase = TP + b * 4096; NT = 64; diff = true; }
;                     else if (u < 1280) { const int v = u - 256; b = v >> 5; h = (v >> 3) & 3; qb = v & 7; rowbase = b * 2048; NT = 32; diff = true; }
;                     else if (u < 1792) { const int v = u - 1280; b = v >> 7; h = (v >> 4) & 7; qb = v & 15; rowbase = TP + b * 4096; NT = 64; diff = false; }
;                     else { const int v = u - 1792; b = v >> 6; h = (v >> 3) & 7; qb = v & 7; rowbase = b * 2048; NT = 32; diff = false; }
;                     const int q0 = qb * 256;
;                     const size_t rq = (size_t)(rowbase + q0) * 64, rk = (size_t)rowbase * 64; constexpr size_t SL = (size_t)T * 64;
;                     if (!diff) {
;                         attn_body::attn_unit<8>((const attn_body::bf16*)(PROJ + h * SL + rq), (const attn_body::bf16*)(PROJ + (8 + (h >> 2)) * SL + rk), (const attn_body::bf16*)(PROJ + (10 + (h >> 2)) * SL + rk),
.LBB0_820:
	s_cmp_lt_i32 s58, 8
	s_cselect_b64 s[0:1], -1, 0
	s_and_b64 s[0:1], s[0:1], s[4:5]
	s_andn2_b64 vcc, exec, s[0:1]
	s_cbranch_vccnz .LBB0_919
	v_readlane_b32 s8, v255, 22
	s_nop 1
	s_cmp_lt_u32 s8, 4
	s_cbranch_scc1 .Lprio_skip1
	s_setprio 1
.Lprio_skip1:
	v_readlane_b32 s8, v255, 6
	global_load_dword v3, v238, s[50:51] offset:256
	v_readlane_b32 s9, v255, 7
	v_readlane_b32 s10, v255, 8
	v_readlane_b32 s11, v255, 9
	v_readlane_b32 s12, v255, 10
	v_readlane_b32 s13, v255, 11
	s_nop 0
	global_load_dword v6, v238, s[8:9] offset:256
	s_nop 0
	global_load_dword v7, v238, s[10:11] offset:256
	s_nop 0
	global_load_dword v8, v238, s[12:13] offset:256
	global_load_dword v9, v238, s[46:47] offset:256
	global_load_dword v10, v238, s[48:49] offset:256
	v_mbcnt_lo_u32_b32 v0, -1, 0
	v_mbcnt_hi_u32_b32 v4, -1, v0
	v_and_b32_e32 v5, 64, v4
	v_xor_b32_e32 v11, 1, v4
	v_add_u32_e32 v5, 64, v5
	v_xor_b32_e32 v12, 2, v4
	v_cmp_lt_i32_e32 vcc, v11, v5
	s_ashr_i32 s3, s2, 31
	v_readlane_b32 s4, v255, 22
	v_xor_b32_e32 v13, 4, v4
	v_cndmask_b32_e32 v11, v4, v11, vcc
	v_cmp_lt_i32_e32 vcc, v12, v5
	v_lshl_or_b32 v236, s4, 5, v239
	s_lshl_b64 s[4:5], s[2:3], 17
	v_xor_b32_e32 v14, 8, v4
	v_cndmask_b32_e32 v12, v4, v12, vcc
	v_cmp_lt_i32_e32 vcc, v13, v5
	v_xor_b32_e32 v15, 16, v4
	s_add_u32 s3, s54, s4
	v_cndmask_b32_e32 v13, v4, v13, vcc
	v_cmp_lt_i32_e32 vcc, v14, v5
	v_xor_b32_e32 v16, 32, v4
	s_addc_u32 s4, s55, s5
	v_cndmask_b32_e32 v14, v4, v14, vcc
	v_cmp_lt_i32_e32 vcc, v15, v5
	s_waitcnt lgkmcnt(0)
	v_lshlrev_b32_e32 v1, 6, v215
	s_add_u32 s10, s3, 0x3400000
	v_cndmask_b32_e32 v15, v4, v15, vcc
	v_cmp_lt_i32_e32 vcc, v16, v5
	v_and_b32_e32 v2, 64, v1
	v_mov_b32_e32 v1, 0
	v_lshlrev_b32_e32 v0, 9, v236
	v_cndmask_b32_e32 v4, v4, v16, vcc
	s_addc_u32 s11, s4, 0
	v_lshlrev_b32_e32 v237, 2, v11
	v_lshlrev_b32_e32 v11, 2, v12
	v_lshlrev_b32_e32 v12, 2, v13
	v_lshlrev_b32_e32 v13, 2, v14
	v_lshlrev_b32_e32 v14, 2, v15
	v_lshlrev_b32_e32 v15, 2, v4
	v_lshl_add_u64 v[4:5], s[10:11], 0, v[0:1]
	v_lshlrev_b32_e32 v0, 1, v2
	v_lshl_add_u64 v[216:217], v[4:5], 0, v[0:1]
	v_readlane_b32 s20, v255, 18
	v_readlane_b32 s21, v255, 19
	v_readlane_b32 s14, v255, 12
	v_readlane_b32 s15, v255, 13
	v_readlane_b32 s16, v255, 14
	v_readlane_b32 s17, v255, 15
	v_readlane_b32 s18, v255, 16
	v_readlane_b32 s19, v255, 17
	v_readlane_b32 s22, v255, 20
	v_readlane_b32 s23, v255, 21
	s_add_u32 s3, s54, 0x80000
	s_movk_i32 s20, 0xe000
	s_mov_b32 s9, 0
	s_addc_u32 s35, s55, 0
	s_mov_b64 s[12:13], 0x500a000
	s_mov_b64 s[16:17], 0x6408000
	s_mov_b64 s[18:19], 0x500e000
	s_mov_b32 s21, -1
	s_mov_b64 s[22:23], 0x4000
	s_mov_b64 s[38:39], 0x2000
	s_mov_b64 s[40:41], 0xa00000
	s_mov_b32 s80, 0xffff0000
	s_mov_b64 s[42:43], 0x6000
	s_mov_b64 s[44:45], 0xa02000
	s_mov_b64 s[46:47], 0x8000
	s_mov_b64 s[48:49], 0xa000
	v_mov_b32_e32 v239, 0x3727c5ac
	v_lshlrev_b32_e32 v222, 1, v2
	s_movk_i32 s81, 0x7fff
	s_mov_b32 s82, 0
	s_waitcnt vmcnt(0)
	v_mul_f32_e32 v0, v3, v6
	ds_bpermute_b32 v0, v237, v0
	v_mul_f32_e32 v4, v7, v8
	v_and_b32_e32 v5, 0x7fffffff, v9
	v_and_b32_e32 v16, 0x7fffffff, v10
	ds_bpermute_b32 v4, v237, v4
	ds_bpermute_b32 v5, v237, v5
	ds_bpermute_b32 v16, v237, v16
	v_max_f32_e64 v9, |v9|, |v9|
	s_waitcnt lgkmcnt(3)
	v_fmac_f32_e32 v0, v3, v6
	s_waitcnt lgkmcnt(2)
	v_fmac_f32_e32 v4, v7, v8
	s_waitcnt lgkmcnt(1)
	v_max_f32_e32 v3, v5, v5
	v_max_f32_e64 v10, |v10|, |v10|
	s_waitcnt lgkmcnt(0)
	v_max_f32_e32 v5, v16, v16
	ds_bpermute_b32 v6, v11, v0
	ds_bpermute_b32 v7, v11, v4
	v_max_f32_e32 v3, v9, v3
	v_max_f32_e32 v5, v10, v5
	ds_bpermute_b32 v8, v11, v3
	ds_bpermute_b32 v9, v11, v5
	s_waitcnt lgkmcnt(3)
	v_add_f32_e32 v0, v0, v6
	s_waitcnt lgkmcnt(2)
	v_add_f32_e32 v4, v4, v7
	ds_bpermute_b32 v6, v12, v0
	ds_bpermute_b32 v7, v12, v4
	s_waitcnt lgkmcnt(3)
	v_max_f32_e32 v8, v8, v8
	s_waitcnt lgkmcnt(2)
	v_max_f32_e32 v9, v9, v9
	v_max_f32_e32 v3, v3, v8
	v_max_f32_e32 v5, v5, v9
	ds_bpermute_b32 v8, v12, v3
	ds_bpermute_b32 v9, v12, v5
	s_waitcnt lgkmcnt(3)
	v_add_f32_e32 v0, v0, v6
	s_waitcnt lgkmcnt(2)
	v_add_f32_e32 v4, v4, v7
	ds_bpermute_b32 v6, v13, v0
	ds_bpermute_b32 v7, v13, v4
	s_waitcnt lgkmcnt(3)
	v_max_f32_e32 v8, v8, v8
	s_waitcnt lgkmcnt(2)
	v_max_f32_e32 v9, v9, v9
	v_max_f32_e32 v3, v3, v8
	v_max_f32_e32 v5, v5, v9
	ds_bpermute_b32 v8, v13, v3
	ds_bpermute_b32 v9, v13, v5
	s_waitcnt lgkmcnt(3)
	v_add_f32_e32 v0, v0, v6
	s_waitcnt lgkmcnt(2)
	v_add_f32_e32 v4, v4, v7
	ds_bpermute_b32 v6, v14, v0
	ds_bpermute_b32 v7, v14, v4
	s_waitcnt lgkmcnt(3)
	v_max_f32_e32 v8, v8, v8
	s_waitcnt lgkmcnt(2)
	v_max_f32_e32 v9, v9, v9
	v_max_f32_e32 v3, v3, v8
	v_max_f32_e32 v5, v5, v9
	ds_bpermute_b32 v8, v14, v3
	ds_bpermute_b32 v9, v14, v5
	s_waitcnt lgkmcnt(3)
	v_add_f32_e32 v0, v0, v6
	s_waitcnt lgkmcnt(2)
	v_add_f32_e32 v4, v4, v7
	ds_bpermute_b32 v6, v15, v0
	ds_bpermute_b32 v7, v15, v4
	s_waitcnt lgkmcnt(3)
	v_max_f32_e32 v8, v8, v8
	s_waitcnt lgkmcnt(2)
	v_max_f32_e32 v9, v9, v9
	v_max_f32_e32 v3, v3, v8
	v_max_f32_e32 v5, v5, v9
	s_waitcnt lgkmcnt(1)
	v_add_f32_e32 v0, v0, v6
	s_waitcnt lgkmcnt(0)
	v_add_f32_e32 v4, v4, v7
	ds_bpermute_b32 v6, v15, v3
	ds_bpermute_b32 v7, v15, v5
	v_mul_f32_e32 v0, 0x3fb8aa3b, v0
	v_mul_f32_e32 v4, 0x3fb8aa3b, v4
	v_exp_f32_e32 v8, v0
	v_exp_f32_e32 v4, v4
	s_waitcnt lgkmcnt(1)
	v_max_f32_e32 v6, v6, v6
	s_waitcnt lgkmcnt(0)
	v_max_f32_e32 v7, v7, v7
	v_max_f32_e32 v3, v3, v6
	v_sub_f32_e32 v4, v8, v4
	v_lshlrev_b32_e32 v0, 2, v2
	v_max_f32_e32 v5, v5, v7
	v_add_f32_e32 v218, 0x3eb60549, v4
	v_mul_f32_e32 v3, 0x413a82f9, v3
	v_mul_f32_e32 v238, v5, v3
	v_lshl_add_u64 v[220:221], s[14:15], 0, v[0:1]
	v_mov_b32_e32 v219, v218
	s_branch .LBB0_823

; #define SEAM(k) do { if (IN(k) && IN((k) + 1)) { if ((k) == 0) cg::this_grid().sync(); else xcd_barrier(bar); } } while (0)
; __device__ __forceinline__ void xcd_barrier(const XcdBarrier& b) {
;     asm volatile("s_waitcnt vmcnt(0)" ::: "memory");
;     __syncthreads();
;     if (threadIdx.x == 0) {
;         unsigned* bar = b.bar;
;         __builtin_amdgcn_s_waitcnt(0);
;         unsigned nloc = b.st[0], nx = b.st[1];
;         if (nloc == 0u) { xcd_barrier_complete(bar, b.x, nloc, nx); b.st[0] = nloc; b.st[1] = nx; }
; __global__ void __launch_bounds__(NWAVES * 64, 2) mk_fwd(Args args) {
;     ...
;     SEAM(7);
.LBB0_919:
	s_setprio 0
	s_cmp_gt_i32 s59, 8
	s_cselect_b64 s[4:5], -1, 0
	s_and_b64 s[0:1], s[0:1], s[4:5]
	s_andn2_b64 vcc, exec, s[0:1]
	s_cbranch_vccnz .LBB0_973
	s_waitcnt vmcnt(0)
	s_waitcnt vmcnt(0) lgkmcnt(0)
	s_barrier
	s_mov_b64 s[0:1], exec
	v_readlane_b32 s6, v255, 4
	v_readlane_b32 s7, v255, 5
	s_and_b64 s[6:7], s[0:1], s[6:7]
	s_mov_b64 exec, s[6:7]
	s_cbranch_execz .LBB0_972
	s_add_i32 s3, 0, 0x20040
	v_mov_b32_e32 v0, s3
	s_waitcnt vmcnt(0) expcnt(0) lgkmcnt(0)
	ds_read_b32 v2, v0
	s_add_i32 s3, 0, 0x20044
	v_mov_b32_e32 v0, s3
	ds_read_b32 v0, v0
	s_waitcnt lgkmcnt(1)
	v_cmp_ne_u32_e32 vcc, 0, v2
	s_cbranch_vccnz .LBB0_936
	v_readlane_b32 s6, v255, 0
	v_readlane_b32 s7, v255, 1
	s_load_dwordx2 s[10:11], s[6:7], 0x4
	s_add_u32 s6, s54, 0x100200
	s_addc_u32 s7, s55, 0
	s_add_u32 s8, s54, 0x100400
	s_addc_u32 s9, s55, 0
	s_waitcnt lgkmcnt(0)
	s_mul_i32 s3, s10, s33
	s_add_u32 s10, s54, 0x100500
	s_mul_i32 s3, s3, s11
	s_addc_u32 s11, s55, 0
	s_add_u32 s12, s54, 0x100600
	s_addc_u32 s13, s55, 0
	s_add_u32 s16, s54, 0x100700
	s_addc_u32 s17, s55, 0
	s_add_u32 s18, s54, 0x100800
	s_addc_u32 s19, s55, 0
	s_add_u32 s20, s54, 0x100900
	s_addc_u32 s21, s55, 0
	s_add_u32 s22, s54, 0x100a00
	s_addc_u32 s23, s55, 0
	s_add_u32 s38, s54, 0x100b00
	s_addc_u32 s39, s55, 0
	s_add_u32 s40, s54, 0x100c00
	s_addc_u32 s41, s55, 0
	s_add_u32 s42, s54, 0x100d00
	s_addc_u32 s43, s55, 0
	s_add_u32 s44, s54, 0x100e00
	s_addc_u32 s45, s55, 0
	s_add_u32 s46, s54, 0x100f00
	s_addc_u32 s47, s55, 0
	s_add_u32 s48, s54, 0x101000
	s_addc_u32 s49, s55, 0
	s_add_u32 s50, s54, 0x101100
	s_addc_u32 s51, s55, 0
	s_add_u32 s64, s54, 0x101200
	s_addc_u32 s65, s55, 0
	s_add_u32 s66, s54, 0x101300
	s_addc_u32 s67, s55, 0
	s_mov_b32 s14, 1
	v_mov_b32_e32 v16, 0
	s_branch .LBB0_924
